# v31 combined + HGRN chain prologue: the first chunk's 26 gate/query loads issued together (counted vmcnt) instead of 13 dependent round trips
# speedup vs baseline: 1.0056x; 1.0012x over previous
; __device__ __forceinline__ void hgrn_chain_ws(const Params& p, int l, int ch, LAS unsigned char* lds, const int tid) {
;     ...
;         float lb;
;         {
;             const float* raw = (dir ? p.lbb : p.lbf) + head * 128 + k;
;             const float a0 = raw[0], a1 = raw[512], a2 = raw[1024], a3 = raw[1536];
;             const float mx = fmaxf(fmaxf(a0, a1), fmaxf(a2, a3));
;             const float e0 = __expf(a0 - mx), e1 = __expf(a1 - mx), e2 = __expf(a2 - mx), e3 = __expf(a3 - mx);
;             float num = 0.f; if (l >= 1) num += e1; if (l >= 2) num += e2; if (l >= 3) num += e3;
;             lb = num / ((e0 + e1) + (e2 + e3));
;         }
;         const float oml = 1.0f - lb;
;         unsigned voffL[16];
; #pragma unroll
;         for (int e = 0; e < 16; ++e) { const int rl = dir ? (31 - 16 * th - e) : (16 * th + e); voffL[e] = (unsigned)(rl * (PJP * 2) + k * 2); }
;         unsigned rq[16], rf[16], ri[16];
;         float q[16], kk[16], bb[16]; unsigned vr[16];
.LBB0_95:
	v_readlane_b32 s44, v253, 36
	s_and_b64 vcc, exec, s[40:41]
	v_readlane_b32 s20, v253, 41
	v_readlane_b32 s21, v253, 39
	v_readlane_b32 s45, v253, 37
	v_readlane_b32 s39, v253, 48
	s_mov_b32 s46, 0x5040100
	s_cbranch_vccz .LBB0_105
	v_readlane_b32 s0, v253, 38
	s_add_u32 s0, s10, s0
	s_addc_u32 s1, s11, 0
	s_load_dwordx2 s[0:1], s[0:1], 0x0
	v_readlane_b32 s9, v254, 31
	v_and_b32_e32 v67, 0x7f, v174
	v_lshlrev_b32_e32 v34, 2, v67
	v_mov_b32_e32 v35, v161
	s_waitcnt lgkmcnt(0)
	s_add_u32 s0, s0, s9
	s_addc_u32 s1, s1, 0
	s_waitcnt vmcnt(1)
	v_lshl_add_u64 v[0:1], s[0:1], 0, v[34:35]
	global_load_dword v2, v34, s[0:1]
	global_load_dword v3, v34, s[0:1] offset:2048
	s_movk_i32 s0, 0x1000
	v_add_co_u32_e32 v0, vcc, s0, v0
	s_cmp_lg_u32 s28, 0
	s_nop 0
	v_addc_co_u32_e32 v1, vcc, 0, v1, vcc
	global_load_dword v4, v[0:1], off
	global_load_dword v5, v[0:1], off offset:2048
	s_cselect_b64 vcc, -1, 0
	s_cmp_gt_u32 s28, 1
	v_readlane_b32 s10, v253, 32
	v_readlane_b32 s16, v253, 34
	v_readlane_b32 s11, v253, 33
	v_readlane_b32 s17, v253, 35
	v_add_u32_e32 v64, 0, v34
	v_lshl_add_u32 v69, v174, 2, 0
	s_movk_i32 s66, 0x2100
	s_waitcnt vmcnt(1)
	v_max_f32_e32 v1, v4, v4
	s_waitcnt vmcnt(0)
	v_max_f32_e32 v0, v5, v5
	v_max_f32_e32 v0, v1, v0
	v_max3_f32 v6, v2, v3, v0
	v_sub_f32_e32 v1, v3, v6
	v_mul_f32_e32 v1, 0x3fb8aa3b, v1
	v_sub_f32_e32 v0, v2, v6
	v_exp_f32_e32 v2, v1
	v_sub_f32_e32 v1, v4, v6
	v_mul_f32_e32 v1, 0x3fb8aa3b, v1
	v_exp_f32_e32 v1, v1
	v_sub_f32_e32 v3, v5, v6
	v_mul_f32_e32 v0, 0x3fb8aa3b, v0
	v_mul_f32_e32 v3, 0x3fb8aa3b, v3
	v_exp_f32_e32 v0, v0
	v_exp_f32_e32 v3, v3
	v_add_f32_e32 v4, 0, v2
	v_cndmask_b32_e32 v4, 0, v4, vcc
	s_cselect_b64 vcc, -1, 0
	v_add_f32_e32 v5, v1, v4
	v_cndmask_b32_e32 v4, v4, v5, vcc
	s_cmp_gt_u32 s28, 2
	s_cselect_b64 vcc, -1, 0
	v_add_f32_e32 v5, v3, v4
	v_pk_add_f32 v[0:1], v[0:1], v[2:3]
	v_cndmask_b32_e32 v4, v4, v5, vcc
	v_add_f32_e32 v0, v0, v1
	v_div_scale_f32 v1, s[0:1], v0, v0, v4
	v_rcp_f32_e32 v2, v1
	s_movk_i32 s0, 0x2100
	v_fma_f32 v3, -v1, v2, 1.0
	v_fmac_f32_e32 v2, v3, v2
	v_div_scale_f32 v3, vcc, v4, v0, v4
	v_mul_f32_e32 v5, v3, v2
	v_fma_f32 v6, -v1, v5, v3
	v_fmac_f32_e32 v5, v6, v2
	v_fma_f32 v1, -v1, v5, v3
	v_ashrrev_i32_e32 v3, 3, v174
	v_and_b32_e32 v68, -16, v3
	v_div_fmas_f32 v1, v1, v2, v5
	v_sub_u32_e32 v2, 31, v68
	v_cndmask_b32_e64 v2, v2, v68, s[44:45]
	v_div_fixup_f32 v0, v1, v0, v4
	v_lshlrev_b32_e32 v1, 1, v67
	v_mul_lo_u32 v2, v2, s0
	v_or_b32_e32 v160, v2, v1
	v_or_b32_e32 v2, 1, v68
	v_sub_u32_e32 v4, 31, v2
	v_cndmask_b32_e64 v2, v4, v2, s[44:45]
	v_or_b32_e32 v4, 2, v68
	v_sub_u32_e32 v5, 31, v4
	v_cndmask_b32_e64 v4, v5, v4, s[44:45]
	v_or_b32_e32 v5, 3, v68
	v_sub_u32_e32 v6, 31, v5
	v_cndmask_b32_e64 v5, v6, v5, s[44:45]
	v_mul_lo_u32 v5, v5, s0
	v_or_b32_e32 v6, v5, v1
	v_or_b32_e32 v5, 4, v68
	v_sub_u32_e32 v7, 31, v5
	v_cndmask_b32_e64 v5, v7, v5, s[44:45]
	v_mul_lo_u32 v5, v5, s0
	v_or_b32_e32 v8, v5, v1
	v_or_b32_e32 v5, 5, v68
	v_sub_u32_e32 v7, 31, v5
	v_cndmask_b32_e64 v5, v7, v5, s[44:45]
	v_mul_lo_u32 v5, v5, s0
	v_or_b32_e32 v10, v5, v1
	v_or_b32_e32 v5, 6, v68
	v_sub_u32_e32 v7, 31, v5
	v_cndmask_b32_e64 v5, v7, v5, s[44:45]
	v_mul_lo_u32 v5, v5, s0
	v_or_b32_e32 v12, v5, v1
	v_or_b32_e32 v5, 7, v68
	v_sub_u32_e32 v7, 31, v5
	v_cndmask_b32_e64 v5, v7, v5, s[44:45]
	v_mul_lo_u32 v5, v5, s0
	v_or_b32_e32 v14, v5, v1
	v_or_b32_e32 v5, 8, v68
	v_sub_u32_e32 v7, 31, v5
	v_cndmask_b32_e64 v5, v7, v5, s[44:45]
	v_mul_lo_u32 v5, v5, s0
	v_or_b32_e32 v16, v5, v1
	v_or_b32_e32 v5, 9, v68
	v_sub_u32_e32 v7, 31, v5
	v_cndmask_b32_e64 v5, v7, v5, s[44:45]
	v_mul_lo_u32 v5, v5, s0
	v_or_b32_e32 v18, v5, v1
	v_or_b32_e32 v5, 10, v68
	v_sub_u32_e32 v7, 31, v5
	v_cndmask_b32_e64 v5, v7, v5, s[44:45]
	v_mul_lo_u32 v5, v5, s0
	v_or_b32_e32 v20, v5, v1
	v_or_b32_e32 v5, 11, v68
	v_sub_u32_e32 v7, 31, v5
	v_cndmask_b32_e64 v5, v7, v5, s[44:45]
	v_mul_lo_u32 v5, v5, s0
	v_or_b32_e32 v22, v5, v1
	v_or_b32_e32 v5, 12, v68
	v_sub_u32_e32 v7, 31, v5
	v_cndmask_b32_e64 v5, v7, v5, s[44:45]
	v_mul_lo_u32 v5, v5, s0
	v_or_b32_e32 v24, v5, v1
	v_or_b32_e32 v5, 13, v68
	v_sub_u32_e32 v7, 31, v5
	v_cndmask_b32_e64 v5, v7, v5, s[44:45]
	v_mul_lo_u32 v5, v5, s0
	v_or_b32_e32 v26, v5, v1
	v_or_b32_e32 v5, 14, v68
	v_sub_u32_e32 v7, 31, v5
	v_cndmask_b32_e64 v5, v7, v5, s[44:45]
	v_mul_lo_u32 v5, v5, s0
	v_or_b32_e32 v3, 15, v3
	v_or_b32_e32 v28, v5, v1
	v_sub_u32_e32 v5, 31, v3
	v_mul_lo_u32 v2, v2, s0
	v_cndmask_b32_e64 v3, v5, v3, s[44:45]
	v_or_b32_e32 v2, v2, v1
	v_mul_lo_u32 v4, v4, s0
	v_mul_lo_u32 v3, v3, s0
	v_or_b32_e32 v4, v4, v1
	v_or_b32_e32 v30, v3, v1
	global_load_ushort v17, v160, s[10:11] offset:3072
	global_load_ushort v19, v2, s[10:11] offset:3072
	global_load_ushort v21, v4, s[10:11] offset:3072
	global_load_ushort v23, v6, s[10:11] offset:3072
	global_load_ushort v25, v8, s[10:11] offset:3072
	global_load_ushort v27, v10, s[10:11] offset:3072
	global_load_ushort v29, v12, s[10:11] offset:3072
	global_load_ushort v31, v14, s[10:11] offset:3072
	global_load_ushort v1, v16, s[10:11] offset:3072
	global_load_ushort v3, v18, s[10:11] offset:3072
	global_load_ushort v5, v20, s[10:11] offset:3072
	global_load_ushort v7, v22, s[10:11] offset:3072
	global_load_ushort v9, v24, s[10:11] offset:3072
	global_load_ushort v11, v26, s[10:11] offset:3072
	global_load_ushort v13, v28, s[10:11] offset:3072
	global_load_ushort v15, v30, s[10:11] offset:3072
	global_load_ushort v176, v2, s[16:17]
	global_load_ushort v177, v160, s[16:17]
	global_load_ushort v178, v2, s[10:11]
	global_load_ushort v179, v160, s[10:11]
	global_load_ushort v180, v4, s[16:17]
	global_load_ushort v181, v6, s[16:17]
	global_load_ushort v182, v4, s[10:11]
	global_load_ushort v183, v6, s[10:11]
	global_load_ushort v184, v8, s[16:17]
	global_load_ushort v185, v10, s[16:17]
	global_load_ushort v186, v8, s[10:11]
	global_load_ushort v187, v10, s[10:11]
	global_load_ushort v188, v12, s[16:17]
	global_load_ushort v189, v14, s[16:17]
	global_load_ushort v190, v12, s[10:11]
	global_load_ushort v191, v14, s[10:11]
	global_load_ushort v192, v16, s[16:17]
	global_load_ushort v193, v18, s[16:17]
	global_load_ushort v194, v16, s[10:11]
	global_load_ushort v195, v18, s[10:11]
	global_load_ushort v196, v20, s[16:17]
	global_load_ushort v197, v22, s[16:17]
	global_load_ushort v198, v20, s[10:11]
	global_load_ushort v199, v22, s[10:11]
	global_load_ushort v200, v24, s[16:17]
	global_load_ushort v201, v26, s[16:17]
	v_sub_f32_e32 v32, 1.0, v0
	s_movk_i32 s0, 0x7f
	v_cmp_lt_u32_e64 s[42:43], s0, v174
	s_movk_i32 s0, 0x80
	v_cmp_gt_u32_e32 vcc, s0, v174
	s_movk_i32 s0, 0x88
	s_waitcnt vmcnt(25)
	v_lshlrev_b32_e32 v35, 16, v176
	s_waitcnt vmcnt(24)
	v_lshlrev_b32_e32 v34, 16, v177
	v_pk_fma_f32 v[34:35], v[32:33], v[34:35], v[0:1] op_sel_hi:[0,1,0]
	v_log_f32_e32 v33, v34
	v_pk_add_f32 v[56:57], v[34:35], 1.0 op_sel_hi:[1,0] neg_lo:[1,0] neg_hi:[1,0]
	v_max_f32_e32 v33, 0xc0fccccd, v33
	v_add_f32_e32 v83, 0, v33
	v_log_f32_e32 v33, v35
	s_nop 0
	v_max_f32_e32 v33, 0xc0fccccd, v33
	v_add_f32_e32 v84, v33, v83
	s_waitcnt vmcnt(23)
	v_lshlrev_b32_e32 v61, 16, v178
	s_waitcnt vmcnt(22)
	v_lshlrev_b32_e32 v60, 16, v179
	v_mul_lo_u32 v33, v68, s0
	v_or_b32_e32 v70, v33, v67
	v_lshl_add_u32 v33, v70, 1, 0
	s_waitcnt vmcnt(21)
	v_lshlrev_b32_e32 v34, 16, v180
	s_waitcnt vmcnt(20)
	v_lshlrev_b32_e32 v35, 16, v181
	v_pk_fma_f32 v[34:35], v[32:33], v[34:35], v[0:1] op_sel_hi:[0,1,0]
	v_log_f32_e32 v36, v34
	v_log_f32_e32 v37, v35
	v_pk_add_f32 v[54:55], v[34:35], 1.0 op_sel_hi:[1,0] neg_lo:[1,0] neg_hi:[1,0]
	v_max_f32_e32 v36, 0xc0fccccd, v36
	v_max_f32_e32 v37, 0xc0fccccd, v37
	v_add_f32_e32 v82, v36, v84
	v_add_f32_e32 v81, v37, v82
	s_waitcnt vmcnt(19)
	v_lshlrev_b32_e32 v58, 16, v182
	s_waitcnt vmcnt(18)
	v_lshlrev_b32_e32 v59, 16, v183
	s_waitcnt vmcnt(17)
	v_lshlrev_b32_e32 v34, 16, v184
	s_waitcnt vmcnt(16)
	v_lshlrev_b32_e32 v35, 16, v185
	v_pk_fma_f32 v[34:35], v[32:33], v[34:35], v[0:1] op_sel_hi:[0,1,0]
	v_log_f32_e32 v36, v34
	v_log_f32_e32 v37, v35
	v_pk_add_f32 v[50:51], v[34:35], 1.0 op_sel_hi:[1,0] neg_lo:[1,0] neg_hi:[1,0]
	v_max_f32_e32 v36, 0xc0fccccd, v36
	v_max_f32_e32 v37, 0xc0fccccd, v37
	v_add_f32_e32 v80, v81, v36
	v_add_f32_e32 v79, v80, v37
	s_waitcnt vmcnt(15)
	v_lshlrev_b32_e32 v52, 16, v186
	s_waitcnt vmcnt(14)
	v_lshlrev_b32_e32 v53, 16, v187
	s_waitcnt vmcnt(13)
	v_lshlrev_b32_e32 v34, 16, v188
	s_waitcnt vmcnt(12)
	v_lshlrev_b32_e32 v35, 16, v189
	v_pk_fma_f32 v[34:35], v[32:33], v[34:35], v[0:1] op_sel_hi:[0,1,0]
	v_log_f32_e32 v36, v34
	v_log_f32_e32 v37, v35
	v_pk_add_f32 v[46:47], v[34:35], 1.0 op_sel_hi:[1,0] neg_lo:[1,0] neg_hi:[1,0]
	v_max_f32_e32 v36, 0xc0fccccd, v36
	v_max_f32_e32 v37, 0xc0fccccd, v37
	v_add_f32_e32 v78, v79, v36
	v_add_f32_e32 v77, v78, v37
	s_waitcnt vmcnt(11)
	v_lshlrev_b32_e32 v48, 16, v190
	s_waitcnt vmcnt(10)
	v_lshlrev_b32_e32 v49, 16, v191
	s_waitcnt vmcnt(9)
	v_lshlrev_b32_e32 v34, 16, v192
	s_waitcnt vmcnt(8)
	v_lshlrev_b32_e32 v35, 16, v193
	v_pk_fma_f32 v[34:35], v[32:33], v[34:35], v[0:1] op_sel_hi:[0,1,0]
	v_log_f32_e32 v36, v34
	v_log_f32_e32 v37, v35
	v_pk_add_f32 v[42:43], v[34:35], 1.0 op_sel_hi:[1,0] neg_lo:[1,0] neg_hi:[1,0]
	v_max_f32_e32 v36, 0xc0fccccd, v36
	v_max_f32_e32 v37, 0xc0fccccd, v37
	v_add_f32_e32 v76, v77, v36
	v_add_f32_e32 v75, v76, v37
	s_waitcnt vmcnt(7)
	v_lshlrev_b32_e32 v44, 16, v194
	s_waitcnt vmcnt(6)
	v_lshlrev_b32_e32 v45, 16, v195
	s_waitcnt vmcnt(5)
	v_lshlrev_b32_e32 v34, 16, v196
	s_waitcnt vmcnt(4)
	v_lshlrev_b32_e32 v35, 16, v197
	v_pk_fma_f32 v[34:35], v[32:33], v[34:35], v[0:1] op_sel_hi:[0,1,0]
	v_log_f32_e32 v36, v34
	v_log_f32_e32 v37, v35
	v_pk_add_f32 v[38:39], v[34:35], 1.0 op_sel_hi:[1,0] neg_lo:[1,0] neg_hi:[1,0]
	v_max_f32_e32 v36, 0xc0fccccd, v36
	v_max_f32_e32 v37, 0xc0fccccd, v37
	v_add_f32_e32 v74, v75, v36
	v_add_f32_e32 v73, v74, v37
	s_waitcnt vmcnt(3)
	v_lshlrev_b32_e32 v40, 16, v198
	s_waitcnt vmcnt(2)
	v_lshlrev_b32_e32 v41, 16, v199
	s_waitcnt vmcnt(1)
	v_lshlrev_b32_e32 v34, 16, v200
	s_waitcnt vmcnt(0)
	v_lshlrev_b32_e32 v35, 16, v201
	v_pk_fma_f32 v[34:35], v[32:33], v[34:35], v[0:1] op_sel_hi:[0,1,0]
	v_log_f32_e32 v36, v34
	v_log_f32_e32 v37, v35
	v_pk_add_f32 v[34:35], v[34:35], 1.0 op_sel_hi:[1,0] neg_lo:[1,0] neg_hi:[1,0]
	v_max_f32_e32 v36, 0xc0fccccd, v36
	v_max_f32_e32 v37, 0xc0fccccd, v37
	v_add_f32_e32 v72, v73, v36
	v_add_f32_e32 v71, v72, v37
	global_load_ushort v36, v24, s[10:11]
	global_load_ushort v37, v26, s[10:11]
	global_load_ushort v62, v28, s[16:17]
	global_load_ushort v63, v30, s[16:17]
	global_load_ushort v87, v28, s[10:11]
	global_load_ushort v88, v30, s[10:11]
	s_waitcnt vmcnt(5)
	v_lshlrev_b32_e32 v36, 16, v36
	s_waitcnt vmcnt(3)
	v_lshlrev_b32_e32 v62, 16, v62
	s_waitcnt vmcnt(2)
	v_lshlrev_b32_e32 v63, 16, v63
	v_pk_fma_f32 v[62:63], v[32:33], v[62:63], v[0:1] op_sel_hi:[0,1,0]
	v_log_f32_e32 v65, v62
	v_log_f32_e32 v66, v63
	v_lshlrev_b32_e32 v37, 16, v37
	v_pk_add_f32 v[62:63], v[62:63], 1.0 op_sel_hi:[1,0] neg_lo:[1,0] neg_hi:[1,0]
	v_max_f32_e32 v65, 0xc0fccccd, v65
	v_max_f32_e32 v66, 0xc0fccccd, v66
	v_add_f32_e32 v86, v71, v65
	v_add_f32_e32 v85, v86, v66
	ds_write_b32 v69, v85 offset:49664
	s_waitcnt lgkmcnt(0)
	s_barrier
	ds_read2st64_b32 v[64:65], v64 offset0:194 offset1:196
	s_waitcnt lgkmcnt(0)
	v_cndmask_b32_e64 v89, v64, 0, vcc
	v_add_f32_e32 v83, v83, v89
	v_add_f32_e32 v84, v84, v89
	v_sub_f32_e32 v83, v83, v64
	v_sub_f32_e32 v84, v84, v64
	v_exp_f32_e32 v90, v83
	v_exp_f32_e32 v91, v84
	v_add_f32_e32 v65, v64, v65
	v_sub_f32_e32 v66, v65, v64
	v_exp_f32_e32 v66, v66
	v_pk_mul_f32 v[60:61], v[90:91], v[60:61]
	v_exp_f32_e64 v90, -v83
	v_exp_f32_e64 v91, -v84
	v_cvt_pk_bf16_f32 v60, v60, v61
	v_pk_mul_f32 v[56:57], v[56:57], v[90:91]
	s_nop 0
	v_cvt_pk_bf16_f32 v61, v56, v57
	ds_write_b16 v33, v60 offset:8704
	ds_write_b16_d16_hi v33, v60 offset:8976
	ds_write_b16 v33, v61 offset:17408
	ds_write_b16_d16_hi v33, v61 offset:17680
	v_add_f32_e32 v60, v82, v89
	v_sub_f32_e32 v82, v60, v64
	v_add_f32_e32 v60, v81, v89
	v_sub_f32_e32 v81, v60, v64
	v_exp_f32_e32 v60, v82
	v_exp_f32_e32 v61, v81
	v_pk_mul_f32 v[56:57], v[66:67], v[56:57] op_sel_hi:[0,1]
	v_pk_mul_f32 v[58:59], v[60:61], v[58:59]
	v_exp_f32_e64 v60, -v82
	v_exp_f32_e64 v61, -v81
	v_cvt_pk_bf16_f32 v58, v58, v59
	v_pk_mul_f32 v[54:55], v[54:55], v[60:61]
	s_nop 0
	v_cvt_pk_bf16_f32 v59, v54, v55
	ds_write_b16 v33, v58 offset:9248
	ds_write_b16_d16_hi v33, v58 offset:9520
	ds_write_b16 v33, v59 offset:17952
	ds_write_b16_d16_hi v33, v59 offset:18224
	v_add_f32_e32 v58, v80, v89
	v_sub_f32_e32 v60, v58, v64
	v_add_f32_e32 v58, v79, v89
	v_sub_f32_e32 v61, v58, v64
	v_exp_f32_e32 v58, v60
	v_exp_f32_e32 v59, v61
	v_pk_mul_f32 v[54:55], v[66:67], v[54:55] op_sel_hi:[0,1]
	v_pk_mul_f32 v[52:53], v[58:59], v[52:53]
	v_exp_f32_e64 v58, -v60
	v_exp_f32_e64 v59, -v61
	v_cvt_pk_bf16_f32 v52, v52, v53
	v_pk_mul_f32 v[50:51], v[50:51], v[58:59]
	s_nop 0
	v_cvt_pk_bf16_f32 v53, v50, v51
	ds_write_b16 v33, v52 offset:9792
	ds_write_b16_d16_hi v33, v52 offset:10064
	ds_write_b16 v33, v53 offset:18496
	ds_write_b16_d16_hi v33, v53 offset:18768
	v_add_f32_e32 v52, v78, v89
	v_sub_f32_e32 v58, v52, v64
	v_add_f32_e32 v52, v77, v89
	v_sub_f32_e32 v59, v52, v64
	v_exp_f32_e32 v52, v58
	v_exp_f32_e32 v53, v59
	v_pk_mul_f32 v[50:51], v[66:67], v[50:51] op_sel_hi:[0,1]
	v_pk_mul_f32 v[48:49], v[52:53], v[48:49]
	v_exp_f32_e64 v52, -v58
	v_exp_f32_e64 v53, -v59
	v_cvt_pk_bf16_f32 v48, v48, v49
	v_pk_mul_f32 v[46:47], v[46:47], v[52:53]
	s_nop 0
	v_cvt_pk_bf16_f32 v49, v46, v47
	ds_write_b16 v33, v48 offset:10336
	ds_write_b16_d16_hi v33, v48 offset:10608
	ds_write_b16 v33, v49 offset:19040
	ds_write_b16_d16_hi v33, v49 offset:19312
	v_add_f32_e32 v48, v76, v89
	v_sub_f32_e32 v52, v48, v64
	v_add_f32_e32 v48, v75, v89
	v_sub_f32_e32 v53, v48, v64
	v_exp_f32_e32 v48, v52
	v_exp_f32_e32 v49, v53
	v_pk_mul_f32 v[46:47], v[66:67], v[46:47] op_sel_hi:[0,1]
	v_pk_mul_f32 v[44:45], v[48:49], v[44:45]
	v_exp_f32_e64 v48, -v52
	v_exp_f32_e64 v49, -v53
	v_cvt_pk_bf16_f32 v44, v44, v45
	v_mul_u32_u24_e32 v53, 40, v67
	v_pk_mul_f32 v[42:43], v[42:43], v[48:49]
	s_nop 0
	v_cvt_pk_bf16_f32 v45, v42, v43
	ds_write_b16 v33, v44 offset:10880
	ds_write_b16_d16_hi v33, v44 offset:11152
	ds_write_b16 v33, v45 offset:19584
	ds_write_b16_d16_hi v33, v45 offset:19856
	v_add_f32_e32 v44, v74, v89
	v_sub_f32_e32 v48, v44, v64
	v_add_f32_e32 v44, v73, v89
	v_sub_f32_e32 v49, v44, v64
	v_exp_f32_e32 v44, v48
	v_exp_f32_e32 v45, v49
	v_pk_mul_f32 v[42:43], v[66:67], v[42:43] op_sel_hi:[0,1]
	v_pk_mul_f32 v[40:41], v[44:45], v[40:41]
	v_exp_f32_e64 v44, -v48
	v_exp_f32_e64 v45, -v49
	v_cvt_pk_bf16_f32 v40, v40, v41
	v_pk_mul_f32 v[38:39], v[38:39], v[44:45]
	s_nop 0
	v_cvt_pk_bf16_f32 v41, v38, v39
	ds_write_b16 v33, v40 offset:11424
	ds_write_b16_d16_hi v33, v40 offset:11696
	ds_write_b16 v33, v41 offset:20128
	ds_write_b16_d16_hi v33, v41 offset:20400
	v_add_f32_e32 v40, v72, v89
	v_sub_f32_e32 v44, v40, v64
	v_add_f32_e32 v40, v71, v89
	v_sub_f32_e32 v45, v40, v64
	v_exp_f32_e32 v40, v44
	v_exp_f32_e32 v41, v45
	v_pk_mul_f32 v[38:39], v[66:67], v[38:39] op_sel_hi:[0,1]
	v_pk_mul_f32 v[36:37], v[40:41], v[36:37]
	v_exp_f32_e64 v40, -v44
	v_exp_f32_e64 v41, -v45
	v_cvt_pk_bf16_f32 v36, v36, v37
	v_pk_mul_f32 v[34:35], v[34:35], v[40:41]
	s_nop 0
	v_cvt_pk_bf16_f32 v37, v34, v35
	v_pk_mul_f32 v[40:41], v[66:67], v[34:35] op_sel_hi:[0,1]
	v_add_f32_e32 v34, v86, v89
	v_sub_f32_e32 v44, v34, v64
	v_add_f32_e32 v34, v89, v85
	v_sub_f32_e32 v45, v34, v64
	v_exp_f32_e32 v34, v44
	v_exp_f32_e32 v35, v45
	ds_write_b16 v33, v36 offset:11968
	ds_write_b16_d16_hi v33, v36 offset:12240
	ds_write_b16 v33, v37 offset:20672
	ds_write_b16_d16_hi v33, v37 offset:20944
	s_waitcnt vmcnt(0)
	v_lshlrev_b32_e32 v37, 16, v88
	v_lshlrev_b32_e32 v36, 16, v87
	v_pk_mul_f32 v[34:35], v[34:35], v[36:37]
	v_exp_f32_e64 v36, -v44
	v_exp_f32_e64 v37, -v45
	v_cvt_pk_bf16_f32 v34, v34, v35
	v_pk_mul_f32 v[36:37], v[62:63], v[36:37]
	s_nop 0
	v_cvt_pk_bf16_f32 v35, v36, v37
	ds_write_b16 v33, v34 offset:12512
	ds_write_b16_d16_hi v33, v34 offset:12784
	ds_write_b16 v33, v35 offset:21216
	ds_write_b16_d16_hi v33, v35 offset:21488
	v_lshl_add_u32 v33, v53, 1, 0
	v_pk_mul_f32 v[44:45], v[66:67], v[36:37] op_sel_hi:[0,1]
	v_lshl_add_u32 v48, v68, 1, v33
	v_cvt_pk_bf16_f32 v34, v56, v57
	v_cvt_pk_bf16_f32 v35, v54, v55
	v_cvt_pk_bf16_f32 v36, v50, v51
	v_cvt_pk_bf16_f32 v37, v46, v47
	ds_write_b128 v48, v[34:37] offset:26112
	v_lshl_or_b32 v34, v19, 16, v17
	v_lshl_or_b32 v35, v23, 16, v21
	v_lshl_or_b32 v36, v27, 16, v25
	v_lshl_or_b32 v37, v31, 16, v29
	ds_write_b128 v48, v[34:37] offset:36352
	v_cvt_pk_bf16_f32 v34, v42, v43
	v_cvt_pk_bf16_f32 v35, v38, v39
	v_cvt_pk_bf16_f32 v36, v40, v41
	v_cvt_pk_bf16_f32 v37, v44, v45
	ds_write_b128 v48, v[34:37] offset:26128
	v_lshl_or_b32 v34, v3, 16, v1
	v_lshl_or_b32 v35, v7, 16, v5
	v_lshl_or_b32 v36, v11, 16, v9
	v_lshl_or_b32 v37, v15, 16, v13
	v_mul_i32_i24_e32 v54, 0xffffffb4, v67
	ds_write_b128 v48, v[34:37] offset:36368
	s_and_saveexec_b64 s[0:1], s[42:43]
	s_xor_b64 s[40:41], exec, s[0:1]
	v_mul_i32_i24_e32 v54, 0xffffffb4, v67
	s_andn2_saveexec_b64 s[40:41], s[40:41]
	s_cbranch_execz .LBB0_100
	v_exp_f32_e32 v1, v64
	v_exp_f32_e32 v3, v65
	s_movk_i32 s0, 0xffb4
	v_mad_i32_i24 v5, v67, s0, v33
	ds_write2st64_b32 v5, v1, v3 offset1:192
